# down-projection split-K units uneven (18/26 K-steps) to balance the residual epilogue
# baseline (speedup 1.0000x reference)
.LBB0_63:
	s_load_dwordx2 s[8:9], s[30:31], 0x170
	s_load_dword s17, s[20:21], 0x0
	s_andn2_b64 vcc, exec, s[0:1]
	s_cbranch_vccnz .LBB0_213
	v_bfe_i32 v5, v1, 27, 1
	v_lshlrev_b32_e32 v4, 4, v1
	v_lshrrev_b32_e32 v5, 22, v5
	v_add_u32_e32 v5, v4, v5
	v_and_b32_e32 v5, 0xfffffc00, v5
	v_ashrrev_i32_e32 v2, 31, v1
	v_sub_u32_e32 v5, v4, v5
	v_lshrrev_b32_e32 v2, 26, v2
	v_lshrrev_b32_e32 v6, 4, v5
	v_add_u32_e32 v2, v1, v2
	v_bitop3_b32 v6, v6, v5, 32 bitop3:0x6c
	v_ashrrev_i32_e32 v5, 31, v5
	v_ashrrev_i32_e32 v2, 6, v2
	v_lshrrev_b32_e32 v5, 26, v5
	v_lshlrev_b32_e32 v7, 3, v2
	v_add_u32_e32 v5, v6, v5
	v_and_b32_e32 v7, 0xfffff0, v7
	v_ashrrev_i32_e32 v13, 6, v5
	v_add_u32_e32 v5, v13, v7
	v_lshlrev_b32_e32 v7, 5, v2
	v_and_b32_e32 v12, 32, v7
	v_mul_i32_i24_e32 v7, 64, v13
	v_sub_u32_e32 v6, v6, v7
	v_mov_b32_e32 v8, 1
	s_movk_i32 s0, 0xb00
	v_ashrrev_i16_sdwa v6, v8, sext(v6) dst_sel:DWORD dst_unused:UNUSED_PAD src0_sel:DWORD src1_sel:BYTE_0
	v_mul_lo_u32 v5, v5, s0
	v_bfe_i32 v14, v6, 0, 16
	v_or_b32_e32 v5, v5, v12
	v_add_u32_e32 v4, 0x2000, v4
	v_add_lshl_u32 v162, v5, v14, 1
	v_ashrrev_i32_e32 v5, 31, v4
	v_lshrrev_b32_e32 v5, 22, v5
	v_add_u32_e32 v5, v4, v5
	v_ashrrev_i32_e32 v15, 10, v5
	v_mul_i32_i24_e32 v5, 0x400, v15
	v_sub_u32_e32 v4, v4, v5
	v_lshrrev_b32_e32 v5, 4, v4
	v_bitop3_b32 v4, v5, v4, 32 bitop3:0x6c
	v_ashrrev_i32_e32 v6, 31, v4
	v_lshrrev_b32_e32 v6, 26, v6
	v_add_u32_e32 v6, v4, v6
	v_lshlrev_b32_e32 v5, 3, v15
	v_ashrrev_i32_e32 v17, 6, v6
	v_and_b32_e32 v6, 0xc0, v6
	v_and_b32_e32 v5, 0xfffff0, v5
	v_sub_u32_e32 v4, v4, v6
	v_add_u32_e32 v5, v17, v5
	v_ashrrev_i16_sdwa v4, v8, sext(v4) dst_sel:DWORD dst_unused:UNUSED_PAD src0_sel:DWORD src1_sel:BYTE_0
	v_bfe_i32 v18, v4, 0, 16
	v_mul_lo_u32 v4, v5, s0
	v_readlane_b32 s0, v254, 7
	s_mul_i32 s0, s0, 0x2c0000
	s_ashr_i32 s12, s16, 6
	s_ashr_i32 s1, s0, 31
	s_ashr_i32 s14, s16, 8
	s_lshl_b32 s18, s12, 10
	s_lshl_b64 s[0:1], s[0:1], 1
	s_add_u32 s0, s28, s0
	s_addc_u32 s1, s29, s1
	s_add_u32 s10, s0, 0x4a20000
	s_addc_u32 s11, s1, 0
	s_mul_i32 s1, s7, 0x160000
	s_mul_hi_i32 s0, s7, 0x160000
	s_add_u32 s1, s10, s1
	s_mul_i32 s15, s55, 0x900
	s_addc_u32 s19, s11, s0
	s_mul_hi_i32 s13, s55, 0x900
	s_add_u32 s0, s1, s15
	s_addc_u32 s1, s19, s13
	s_add_i32 s19, s18, 0
	s_add_i32 m0, s19, 0x10000
	v_lshlrev_b32_e32 v7, 5, v15
	s_mul_i32 s5, s6, 0x160000
	global_load_lds_dwordx4 v162, s[0:1]
	s_add_i32 m0, s19, 0x12000
	v_and_b32_e32 v16, 32, v7
	s_mul_hi_i32 s4, s6, 0x160000
	s_add_u32 s5, s36, s5
	v_or_b32_e32 v4, v4, v16
	s_addc_u32 s27, s37, s4
	v_add_lshl_u32 v164, v4, v18, 1
	s_add_u32 s4, s5, s15
	global_load_lds_dwordx4 v164, s[0:1]
	s_addc_u32 s5, s27, s13
	s_mov_b32 m0, s19
	s_add_i32 s27, s19, 0x2000
	global_load_lds_dwordx4 v162, s[4:5]
	s_mov_b32 m0, s27
	s_add_u32 s46, s0, 0xb0000
	global_load_lds_dwordx4 v164, s[4:5]
	s_addc_u32 s47, s1, 0
	s_add_i32 m0, s19, 0x14000
	v_mov_b32_e32 v163, v3
	global_load_lds_dwordx4 v162, s[46:47]
	s_add_i32 m0, s19, 0x16000
	s_add_u32 s48, s4, 0xb0000
	s_addc_u32 s49, s5, 0
	s_add_i32 s45, s19, 0x4000
	global_load_lds_dwordx4 v164, s[46:47]
	s_mov_b32 m0, s45
	s_add_i32 s46, s19, 0x6000
	global_load_lds_dwordx4 v162, s[48:49]
	s_mov_b32 m0, s46
	v_mov_b32_e32 v165, v3
	global_load_lds_dwordx4 v164, s[48:49]
	v_mov_b32_e32 v219, 1
	v_lshl_add_u64 v[10:11], s[0:1], 0, v[162:163]
	v_lshl_add_u64 v[8:9], s[0:1], 0, v[164:165]
	v_lshl_add_u64 v[6:7], s[4:5], 0, v[162:163]
	s_cmp_lg_u32 s14, 1
	v_lshl_add_u64 v[4:5], s[4:5], 0, v[164:165]
	s_cbranch_scc1 .LBB0_66
	s_barrier

.LBB0_76:
	v_cndmask_b32_e64 v2, 0, 1, s[0:1]
	v_cmp_ne_u32_e64 s[6:7], 1, v2
	s_andn2_b64 vcc, exec, s[0:1]
	s_mul_hi_i32 s1, s54, 0x900
	s_mul_i32 s0, s54, 0x900
	v_mov_b64_e32 v[170:171], v[64:65]
	s_cbranch_vccnz .LBB0_78
	s_mov_b32 s14, 0x160000
	v_mul_hi_i32 v7, v157, s14
	v_mul_lo_u32 v6, v157, s14
	v_lshl_add_u64 v[6:7], s[36:37], 0, v[6:7]
	v_lshl_add_u64 v[170:171], v[6:7], 0, s[0:1]

.LBB0_80:
	s_mov_b64 s[74:75], 0x100
	v_lshl_add_u64 v[62:63], v[4:5], 0, s[74:75]
	v_mov_b32_e32 v4, 0
	s_mov_b32 s0, -2
	v_mov_b32_e32 v5, v4
	v_mov_b32_e32 v6, v4
	v_mov_b32_e32 v7, v4
	v_mov_b32_e32 v8, v4
	v_mov_b32_e32 v9, v4
	v_mov_b32_e32 v10, v4
	v_mov_b32_e32 v11, v4
	v_mov_b32_e32 v20, v4
	v_mov_b32_e32 v21, v4
	v_mov_b32_e32 v22, v4
	v_mov_b32_e32 v23, v4
	v_mov_b32_e32 v24, v4
	v_mov_b32_e32 v25, v4
	v_mov_b32_e32 v26, v4
	v_mov_b32_e32 v27, v4
	v_mov_b32_e32 v38, v4
	v_mov_b32_e32 v39, v4
	v_mov_b32_e32 v40, v4
	v_mov_b32_e32 v41, v4
	v_mov_b32_e32 v42, v4
	v_mov_b32_e32 v43, v4
	v_mov_b32_e32 v44, v4
	v_mov_b32_e32 v45, v4
	v_mov_b32_e32 v54, v4
	v_mov_b32_e32 v55, v4
	v_mov_b32_e32 v56, v4
	v_mov_b32_e32 v57, v4
	v_mov_b32_e32 v58, v4
	v_mov_b32_e32 v59, v4
	v_mov_b32_e32 v60, v4
	v_mov_b32_e32 v61, v4
	v_mov_b32_e32 v12, v4
	v_mov_b32_e32 v13, v4
	v_mov_b32_e32 v14, v4
	v_mov_b32_e32 v15, v4
	v_mov_b32_e32 v16, v4
	v_mov_b32_e32 v17, v4
	v_mov_b32_e32 v18, v4
	v_mov_b32_e32 v19, v4
	v_mov_b32_e32 v28, v4
	v_mov_b32_e32 v29, v4
	v_mov_b32_e32 v30, v4
	v_mov_b32_e32 v31, v4
	v_mov_b32_e32 v32, v4
	v_mov_b32_e32 v33, v4
	v_mov_b32_e32 v34, v4
	v_mov_b32_e32 v35, v4
	v_mov_b32_e32 v46, v4
	v_mov_b32_e32 v47, v4
	v_mov_b32_e32 v48, v4
	v_mov_b32_e32 v49, v4
	v_mov_b32_e32 v50, v4
	v_mov_b32_e32 v51, v4
	v_mov_b32_e32 v52, v4
	v_mov_b32_e32 v53, v4
	v_mov_b32_e32 v70, v4
	v_mov_b32_e32 v71, v4
	v_mov_b32_e32 v72, v4
	v_mov_b32_e32 v73, v4
	v_mov_b32_e32 v78, v4
	v_mov_b32_e32 v79, v4
	v_mov_b32_e32 v80, v4
	v_mov_b32_e32 v81, v4
	s_waitcnt vmcnt(0)
	v_mov_b32_e32 v86, v4
	v_mov_b32_e32 v87, v4
	v_mov_b32_e32 v88, v4
	v_mov_b32_e32 v89, v4
	v_mov_b32_e32 v90, v4
	v_mov_b32_e32 v91, v4
	v_mov_b32_e32 v92, v4
	v_mov_b32_e32 v93, v4
	v_mov_b32_e32 v102, v4
	v_mov_b32_e32 v103, v4
	v_mov_b32_e32 v104, v4
	v_mov_b32_e32 v105, v4
	v_mov_b32_e32 v106, v4
	v_mov_b32_e32 v107, v4
	v_mov_b32_e32 v108, v4
	v_mov_b32_e32 v109, v4
	v_mov_b32_e32 v118, v4
	v_mov_b32_e32 v119, v4
	v_mov_b32_e32 v120, v4
	v_mov_b32_e32 v121, v4
	v_mov_b32_e32 v122, v4
	v_mov_b32_e32 v123, v4
	v_mov_b32_e32 v124, v4
	v_mov_b32_e32 v125, v4
	v_mov_b32_e32 v134, v4
	v_mov_b32_e32 v135, v4
	v_mov_b32_e32 v136, v4
	v_mov_b32_e32 v137, v4
	v_mov_b32_e32 v138, v4
	v_mov_b32_e32 v139, v4
	v_mov_b32_e32 v140, v4
	v_mov_b32_e32 v141, v4
	v_mov_b32_e32 v94, v4
	v_mov_b32_e32 v95, v4
	v_mov_b32_e32 v96, v4
	v_mov_b32_e32 v97, v4
	v_mov_b32_e32 v98, v4
	v_mov_b32_e32 v99, v4
	v_mov_b32_e32 v100, v4
	v_mov_b32_e32 v101, v4
	v_mov_b32_e32 v110, v4
	v_mov_b32_e32 v111, v4
	v_mov_b32_e32 v112, v4
	v_mov_b32_e32 v113, v4
	v_mov_b32_e32 v114, v4
	v_mov_b32_e32 v115, v4
	v_mov_b32_e32 v116, v4
	v_mov_b32_e32 v117, v4
	v_mov_b32_e32 v126, v4
	v_mov_b32_e32 v127, v4
	v_mov_b32_e32 v128, v4
	v_mov_b32_e32 v129, v4
	v_mov_b32_e32 v130, v4
	v_mov_b32_e32 v131, v4
	v_mov_b32_e32 v132, v4
	v_mov_b32_e32 v133, v4
	v_mov_b32_e32 v142, v4
	v_mov_b32_e32 v143, v4
	v_mov_b32_e32 v144, v4
	v_mov_b32_e32 v145, v4
	v_mov_b32_e32 v146, v4
	v_mov_b32_e32 v147, v4
	v_mov_b32_e32 v148, v4
	v_mov_b32_e32 v149, v4
	s_mov_b64 s[14:15], 0xb0000
	s_mov_b64 s[40:41], 0xb0080
	s_cmp_eq_u32 s55, 0
	s_cselect_b32 s98, 14, 22
	s_cselect_b32 s99, 15, 23
.LBB0_81:
	s_add_i32 s1, 0, 0x10000
	v_add_u32_e32 v2, s1, v1
	ds_read_b128 v[82:85], v2
	ds_read_b128 v[150:153], v2 offset:1024
	ds_read_b128 v[158:161], v2 offset:2048
	ds_read_b128 v[178:181], v2 offset:3072
	s_cmp_eq_u32 s0, s98
	v_lshl_add_u64 v[66:67], v[64:65], 0, s[74:75]
	s_cselect_b64 vcc, -1, 0
	v_cndmask_b32_e32 v175, v67, v171, vcc
	v_cndmask_b32_e32 v174, v66, v170, vcc
	v_cndmask_b32_e32 v69, v63, v173, vcc
	v_cndmask_b32_e32 v68, v62, v172, vcc
	v_lshl_add_u64 v[76:77], v[64:65], 0, v[166:167]
	s_add_i32 m0, s19, 0xc000
	ds_read_b128 v[182:185], v155
	ds_read_b128 v[186:189], v155 offset:1024
	ds_read_b128 v[190:193], v155 offset:2048
	ds_read_b128 v[194:197], v155 offset:3072
	ds_read_b128 v[198:201], v155 offset:4096
	ds_read_b128 v[202:205], v155 offset:5120
	ds_read_b128 v[206:209], v155 offset:6144
	ds_read_b128 v[210:213], v155 offset:7168
	global_load_lds_dwordx4 v[76:77], off
	v_lshl_add_u64 v[64:65], v[64:65], 0, v[168:169]
	s_add_i32 m0, s19, 0xe000
	s_nop 0
	global_load_lds_dwordx4 v[64:65], off
	s_waitcnt lgkmcnt(8)
	s_barrier
	s_waitcnt lgkmcnt(0)
	s_setprio 1
	s_waitcnt lgkmcnt(0)
	v_mfma_f32_16x16x32_bf16 v[146:149], v[82:85], v[182:185], v[146:149]
	v_mfma_f32_16x16x32_bf16 v[142:145], v[158:161], v[182:185], v[142:145]
	v_mfma_f32_16x16x32_bf16 v[130:133], v[82:85], v[190:193], v[130:133]
	v_mfma_f32_16x16x32_bf16 v[126:129], v[158:161], v[190:193], v[126:129]
	v_mfma_f32_16x16x32_bf16 v[114:117], v[82:85], v[198:201], v[114:117]
	v_mfma_f32_16x16x32_bf16 v[110:113], v[158:161], v[198:201], v[110:113]
	v_mfma_f32_16x16x32_bf16 v[98:101], v[82:85], v[206:209], v[98:101]
	v_mfma_f32_16x16x32_bf16 v[94:97], v[158:161], v[206:209], v[94:97]
	v_mfma_f32_16x16x32_bf16 v[146:149], v[150:153], v[186:189], v[146:149]
	v_mfma_f32_16x16x32_bf16 v[142:145], v[178:181], v[186:189], v[142:145]
	v_mfma_f32_16x16x32_bf16 v[130:133], v[150:153], v[194:197], v[130:133]
	v_mfma_f32_16x16x32_bf16 v[126:129], v[178:181], v[194:197], v[126:129]
	v_mfma_f32_16x16x32_bf16 v[114:117], v[150:153], v[202:205], v[114:117]
	v_mfma_f32_16x16x32_bf16 v[110:113], v[178:181], v[202:205], v[110:113]
	v_mfma_f32_16x16x32_bf16 v[98:101], v[150:153], v[210:213], v[98:101]
	v_mfma_f32_16x16x32_bf16 v[94:97], v[178:181], v[210:213], v[94:97]
	s_setprio 0
	s_barrier
	s_add_i32 s6, 0, 0x14000
	s_add_i32 s1, s1, s18
	v_add_u32_e32 v2, s6, v1
	v_lshl_add_u64 v[64:65], v[68:69], 0, v[162:163]
	s_mov_b32 m0, s1
	ds_read_b128 v[214:217], v2
	ds_read_b128 v[234:237], v2 offset:1024
	ds_read_b128 v[238:241], v2 offset:2048
	ds_read_b128 v[242:245], v2 offset:3072
	global_load_lds_dwordx4 v[64:65], off
	v_lshl_add_u64 v[230:231], v[68:69], 0, v[164:165]
	s_add_i32 m0, s1, 0x2000
	s_nop 0
	global_load_lds_dwordx4 v[230:231], off
	s_barrier
	s_waitcnt lgkmcnt(0)
	s_setprio 1
	s_waitcnt lgkmcnt(0)
	v_mfma_f32_16x16x32_bf16 v[138:141], v[214:217], v[182:185], v[138:141]
	v_mfma_f32_16x16x32_bf16 v[134:137], v[238:241], v[182:185], v[134:137]
	v_mfma_f32_16x16x32_bf16 v[122:125], v[214:217], v[190:193], v[122:125]
	v_mfma_f32_16x16x32_bf16 v[118:121], v[238:241], v[190:193], v[118:121]
	v_mfma_f32_16x16x32_bf16 v[106:109], v[214:217], v[198:201], v[106:109]
	v_mfma_f32_16x16x32_bf16 v[102:105], v[238:241], v[198:201], v[102:105]
	v_mfma_f32_16x16x32_bf16 v[90:93], v[214:217], v[206:209], v[90:93]
	v_mfma_f32_16x16x32_bf16 v[86:89], v[238:241], v[206:209], v[86:89]
	v_mfma_f32_16x16x32_bf16 v[138:141], v[234:237], v[186:189], v[138:141]
	v_mfma_f32_16x16x32_bf16 v[134:137], v[242:245], v[186:189], v[134:137]
	v_mfma_f32_16x16x32_bf16 v[122:125], v[234:237], v[194:197], v[122:125]
	v_mfma_f32_16x16x32_bf16 v[118:121], v[242:245], v[194:197], v[118:121]
	v_mfma_f32_16x16x32_bf16 v[106:109], v[234:237], v[202:205], v[106:109]
	v_mfma_f32_16x16x32_bf16 v[102:105], v[242:245], v[202:205], v[102:105]
	v_mfma_f32_16x16x32_bf16 v[90:93], v[234:237], v[210:213], v[90:93]
	v_mfma_f32_16x16x32_bf16 v[86:89], v[242:245], v[210:213], v[86:89]
	s_setprio 0
	s_mov_b32 m0, s19
	v_lshl_add_u64 v[246:247], v[174:175], 0, v[162:163]
	s_barrier
	ds_read_b128 v[182:185], v155 offset:16384
	ds_read_b128 v[186:189], v155 offset:17408
	ds_read_b128 v[190:193], v155 offset:18432
	ds_read_b128 v[194:197], v155 offset:19456
	ds_read_b128 v[198:201], v155 offset:20480
	ds_read_b128 v[202:205], v155 offset:21504
	ds_read_b128 v[206:209], v155 offset:22528
	ds_read_b128 v[210:213], v155 offset:23552
	global_load_lds_dwordx4 v[246:247], off
	v_lshl_add_u64 v[248:249], v[174:175], 0, v[164:165]
	s_mov_b32 m0, s27
	s_nop 0
	global_load_lds_dwordx4 v[248:249], off
	s_barrier
	s_waitcnt lgkmcnt(0)
	s_setprio 1
	s_waitcnt lgkmcnt(0)
	v_mfma_f32_16x16x32_bf16 v[76:79], v[82:85], v[182:185], v[78:81]
	v_mfma_f32_16x16x32_bf16 v[70:73], v[158:161], v[182:185], v[70:73]
	v_mfma_f32_16x16x32_bf16 v[50:53], v[82:85], v[190:193], v[50:53]
	v_mfma_f32_16x16x32_bf16 v[46:49], v[158:161], v[190:193], v[46:49]
	v_mfma_f32_16x16x32_bf16 v[32:35], v[82:85], v[198:201], v[32:35]
	v_mfma_f32_16x16x32_bf16 v[28:31], v[158:161], v[198:201], v[28:31]
	v_mfma_f32_16x16x32_bf16 v[16:19], v[82:85], v[206:209], v[16:19]
	v_mfma_f32_16x16x32_bf16 v[12:15], v[158:161], v[206:209], v[12:15]
	v_mfma_f32_16x16x32_bf16 v[76:79], v[150:153], v[186:189], v[76:79]
	v_mfma_f32_16x16x32_bf16 v[70:73], v[178:181], v[186:189], v[70:73]
	v_mfma_f32_16x16x32_bf16 v[50:53], v[150:153], v[194:197], v[50:53]
	v_mfma_f32_16x16x32_bf16 v[46:49], v[178:181], v[194:197], v[46:49]
	v_mfma_f32_16x16x32_bf16 v[32:35], v[150:153], v[202:205], v[32:35]
	v_mfma_f32_16x16x32_bf16 v[28:31], v[178:181], v[202:205], v[28:31]
	v_mfma_f32_16x16x32_bf16 v[16:19], v[150:153], v[210:213], v[16:19]
	v_mfma_f32_16x16x32_bf16 v[12:15], v[178:181], v[210:213], v[12:15]
	s_setprio 0
	s_barrier
	v_lshl_add_u64 v[80:81], v[68:69], 0, s[14:15]
	s_add_i32 s1, s6, s18
	v_lshl_add_u64 v[82:83], v[80:81], 0, v[162:163]
	s_mov_b32 m0, s1
	v_lshl_add_u64 v[80:81], v[80:81], 0, v[164:165]
	global_load_lds_dwordx4 v[82:83], off
	s_add_i32 m0, s1, 0x2000
	s_nop 0
	global_load_lds_dwordx4 v[80:81], off
	s_waitcnt vmcnt(6)
	s_barrier
	s_setprio 1
	v_mfma_f32_16x16x32_bf16 v[58:61], v[214:217], v[182:185], v[58:61]
	v_mfma_f32_16x16x32_bf16 v[54:57], v[238:241], v[182:185], v[54:57]
	v_mfma_f32_16x16x32_bf16 v[42:45], v[214:217], v[190:193], v[42:45]
	v_mfma_f32_16x16x32_bf16 v[38:41], v[238:241], v[190:193], v[38:41]
	v_mfma_f32_16x16x32_bf16 v[24:27], v[214:217], v[198:201], v[24:27]
	v_mfma_f32_16x16x32_bf16 v[20:23], v[238:241], v[198:201], v[20:23]
	v_mfma_f32_16x16x32_bf16 v[8:11], v[214:217], v[206:209], v[8:11]
	v_mfma_f32_16x16x32_bf16 v[4:7], v[238:241], v[206:209], v[4:7]
	v_mfma_f32_16x16x32_bf16 v[58:61], v[234:237], v[186:189], v[58:61]
	v_mfma_f32_16x16x32_bf16 v[54:57], v[242:245], v[186:189], v[54:57]
	v_mfma_f32_16x16x32_bf16 v[42:45], v[234:237], v[194:197], v[42:45]
	v_mfma_f32_16x16x32_bf16 v[38:41], v[242:245], v[194:197], v[38:41]
	v_mfma_f32_16x16x32_bf16 v[24:27], v[234:237], v[202:205], v[24:27]
	v_mfma_f32_16x16x32_bf16 v[20:23], v[242:245], v[202:205], v[20:23]
	v_mfma_f32_16x16x32_bf16 v[8:11], v[234:237], v[210:213], v[8:11]
	v_mfma_f32_16x16x32_bf16 v[4:7], v[242:245], v[210:213], v[4:7]
	s_setprio 0
	s_add_i32 s1, 0, 0x18000
	v_add_u32_e32 v2, s1, v1
	s_barrier
	ds_read_b128 v[82:85], v2
	ds_read_b128 v[150:153], v2 offset:1024
	ds_read_b128 v[158:161], v2 offset:2048
	ds_read_b128 v[178:181], v2 offset:3072
	v_lshl_add_u64 v[80:81], v[174:175], 0, s[14:15]
	s_mov_b32 m0, s45
	v_lshl_add_u64 v[174:175], v[80:81], 0, v[162:163]
	ds_read_b128 v[182:185], v155 offset:32768
	ds_read_b128 v[186:189], v155 offset:33792
	ds_read_b128 v[190:193], v155 offset:34816
	ds_read_b128 v[194:197], v155 offset:35840
	ds_read_b128 v[198:201], v155 offset:36864
	ds_read_b128 v[202:205], v155 offset:37888
	ds_read_b128 v[206:209], v155 offset:38912
	ds_read_b128 v[210:213], v155 offset:39936
	global_load_lds_dwordx4 v[174:175], off
	v_lshl_add_u64 v[80:81], v[80:81], 0, v[164:165]
	s_mov_b32 m0, s46
	s_nop 0
	global_load_lds_dwordx4 v[80:81], off
	s_waitcnt lgkmcnt(8)
	s_barrier
	s_waitcnt lgkmcnt(0)
	s_setprio 1
	s_waitcnt lgkmcnt(0)
	v_mfma_f32_16x16x32_bf16 v[146:149], v[82:85], v[182:185], v[146:149]
	v_mfma_f32_16x16x32_bf16 v[142:145], v[158:161], v[182:185], v[142:145]
	v_mfma_f32_16x16x32_bf16 v[130:133], v[82:85], v[190:193], v[130:133]
	v_mfma_f32_16x16x32_bf16 v[126:129], v[158:161], v[190:193], v[126:129]
	v_mfma_f32_16x16x32_bf16 v[114:117], v[82:85], v[198:201], v[114:117]
	v_mfma_f32_16x16x32_bf16 v[110:113], v[158:161], v[198:201], v[110:113]
	v_mfma_f32_16x16x32_bf16 v[98:101], v[82:85], v[206:209], v[98:101]
	v_mfma_f32_16x16x32_bf16 v[94:97], v[158:161], v[206:209], v[94:97]
	v_mfma_f32_16x16x32_bf16 v[146:149], v[150:153], v[186:189], v[146:149]
	v_mfma_f32_16x16x32_bf16 v[142:145], v[178:181], v[186:189], v[142:145]
	v_mfma_f32_16x16x32_bf16 v[130:133], v[150:153], v[194:197], v[130:133]
	v_mfma_f32_16x16x32_bf16 v[126:129], v[178:181], v[194:197], v[126:129]
	v_mfma_f32_16x16x32_bf16 v[114:117], v[150:153], v[202:205], v[114:117]
	v_mfma_f32_16x16x32_bf16 v[110:113], v[178:181], v[202:205], v[110:113]
	v_mfma_f32_16x16x32_bf16 v[98:101], v[150:153], v[210:213], v[98:101]
	v_mfma_f32_16x16x32_bf16 v[94:97], v[178:181], v[210:213], v[94:97]
	s_setprio 0
	s_barrier
	s_add_i32 s6, 0, 0x1c000
	s_add_i32 s1, s1, s18
	v_add_u32_e32 v2, s6, v1
	v_lshl_add_u64 v[64:65], v[64:65], 0, s[24:25]
	s_mov_b32 m0, s1
	ds_read_b128 v[214:217], v2
	ds_read_b128 v[234:237], v2 offset:1024
	ds_read_b128 v[238:241], v2 offset:2048
	ds_read_b128 v[242:245], v2 offset:3072
	global_load_lds_dwordx4 v[64:65], off
	v_lshl_add_u64 v[64:65], v[230:231], 0, s[24:25]
	s_add_i32 m0, s1, 0x2000
	s_nop 0
	global_load_lds_dwordx4 v[64:65], off
	s_barrier
	s_waitcnt lgkmcnt(0)
	s_setprio 1
	s_waitcnt lgkmcnt(0)
	v_mfma_f32_16x16x32_bf16 v[138:141], v[214:217], v[182:185], v[138:141]
	v_mfma_f32_16x16x32_bf16 v[134:137], v[238:241], v[182:185], v[134:137]
	v_mfma_f32_16x16x32_bf16 v[122:125], v[214:217], v[190:193], v[122:125]
	v_mfma_f32_16x16x32_bf16 v[118:121], v[238:241], v[190:193], v[118:121]
	v_mfma_f32_16x16x32_bf16 v[106:109], v[214:217], v[198:201], v[106:109]
	v_mfma_f32_16x16x32_bf16 v[102:105], v[238:241], v[198:201], v[102:105]
	v_mfma_f32_16x16x32_bf16 v[90:93], v[214:217], v[206:209], v[90:93]
	v_mfma_f32_16x16x32_bf16 v[86:89], v[238:241], v[206:209], v[86:89]
	v_mfma_f32_16x16x32_bf16 v[138:141], v[234:237], v[186:189], v[138:141]
	v_mfma_f32_16x16x32_bf16 v[134:137], v[242:245], v[186:189], v[134:137]
	v_mfma_f32_16x16x32_bf16 v[122:125], v[234:237], v[194:197], v[122:125]
	v_mfma_f32_16x16x32_bf16 v[118:121], v[242:245], v[194:197], v[118:121]
	v_mfma_f32_16x16x32_bf16 v[106:109], v[234:237], v[202:205], v[106:109]
	v_mfma_f32_16x16x32_bf16 v[102:105], v[242:245], v[202:205], v[102:105]
	v_mfma_f32_16x16x32_bf16 v[90:93], v[234:237], v[210:213], v[90:93]
	v_mfma_f32_16x16x32_bf16 v[86:89], v[242:245], v[210:213], v[86:89]
	s_setprio 0
	s_mov_b32 m0, s47
	v_lshl_add_u64 v[64:65], v[246:247], 0, s[24:25]
	s_barrier
	ds_read_b128 v[182:185], v155 offset:49152
	ds_read_b128 v[186:189], v155 offset:50176
	ds_read_b128 v[190:193], v155 offset:51200
	ds_read_b128 v[194:197], v155 offset:52224
	ds_read_b128 v[198:201], v155 offset:53248
	ds_read_b128 v[202:205], v155 offset:54272
	ds_read_b128 v[206:209], v155 offset:55296
	ds_read_b128 v[210:213], v155 offset:56320
	global_load_lds_dwordx4 v[64:65], off
	v_lshl_add_u64 v[64:65], v[248:249], 0, s[24:25]
	s_mov_b32 m0, s48
	s_nop 0
	global_load_lds_dwordx4 v[64:65], off
	s_barrier
	s_waitcnt lgkmcnt(0)
	s_setprio 1
	s_waitcnt lgkmcnt(0)
	v_mfma_f32_16x16x32_bf16 v[76:79], v[82:85], v[182:185], v[76:79]
	v_mfma_f32_16x16x32_bf16 v[70:73], v[158:161], v[182:185], v[70:73]
	v_mfma_f32_16x16x32_bf16 v[50:53], v[82:85], v[190:193], v[50:53]
	v_mfma_f32_16x16x32_bf16 v[46:49], v[158:161], v[190:193], v[46:49]
	v_mfma_f32_16x16x32_bf16 v[32:35], v[82:85], v[198:201], v[32:35]
	v_mfma_f32_16x16x32_bf16 v[28:31], v[158:161], v[198:201], v[28:31]
	v_mfma_f32_16x16x32_bf16 v[16:19], v[82:85], v[206:209], v[16:19]
	v_mfma_f32_16x16x32_bf16 v[12:15], v[158:161], v[206:209], v[12:15]
	v_mfma_f32_16x16x32_bf16 v[78:81], v[150:153], v[186:189], v[76:79]
	v_mfma_f32_16x16x32_bf16 v[70:73], v[178:181], v[186:189], v[70:73]
	v_mfma_f32_16x16x32_bf16 v[50:53], v[150:153], v[194:197], v[50:53]
	v_mfma_f32_16x16x32_bf16 v[46:49], v[178:181], v[194:197], v[46:49]
	v_mfma_f32_16x16x32_bf16 v[32:35], v[150:153], v[202:205], v[32:35]
	v_mfma_f32_16x16x32_bf16 v[28:31], v[178:181], v[202:205], v[28:31]
	v_mfma_f32_16x16x32_bf16 v[16:19], v[150:153], v[210:213], v[16:19]
	v_mfma_f32_16x16x32_bf16 v[12:15], v[178:181], v[210:213], v[12:15]
	s_setprio 0
	s_barrier
	v_lshl_add_u64 v[64:65], v[68:69], 0, s[40:41]
	s_add_i32 s1, s6, s18
	v_lshl_add_u64 v[68:69], v[64:65], 0, v[162:163]
	s_mov_b32 m0, s1
	v_lshl_add_u64 v[64:65], v[64:65], 0, v[164:165]
	global_load_lds_dwordx4 v[68:69], off
	s_add_i32 m0, s1, 0x2000
	s_nop 0
	global_load_lds_dwordx4 v[64:65], off
	s_waitcnt vmcnt(6)
	s_barrier
	s_setprio 1
	v_mfma_f32_16x16x32_bf16 v[58:61], v[214:217], v[182:185], v[58:61]
	v_mfma_f32_16x16x32_bf16 v[54:57], v[238:241], v[182:185], v[54:57]
	v_mfma_f32_16x16x32_bf16 v[42:45], v[214:217], v[190:193], v[42:45]
	v_mfma_f32_16x16x32_bf16 v[38:41], v[238:241], v[190:193], v[38:41]
	v_mfma_f32_16x16x32_bf16 v[24:27], v[214:217], v[198:201], v[24:27]
	v_mfma_f32_16x16x32_bf16 v[20:23], v[238:241], v[198:201], v[20:23]
	v_mfma_f32_16x16x32_bf16 v[8:11], v[214:217], v[206:209], v[8:11]
	v_mfma_f32_16x16x32_bf16 v[4:7], v[238:241], v[206:209], v[4:7]
	v_mfma_f32_16x16x32_bf16 v[58:61], v[234:237], v[186:189], v[58:61]
	v_mfma_f32_16x16x32_bf16 v[54:57], v[242:245], v[186:189], v[54:57]
	v_mfma_f32_16x16x32_bf16 v[42:45], v[234:237], v[194:197], v[42:45]
	v_mfma_f32_16x16x32_bf16 v[38:41], v[242:245], v[194:197], v[38:41]
	v_mfma_f32_16x16x32_bf16 v[24:27], v[234:237], v[202:205], v[24:27]
	v_mfma_f32_16x16x32_bf16 v[20:23], v[242:245], v[202:205], v[20:23]
	v_mfma_f32_16x16x32_bf16 v[8:11], v[234:237], v[210:213], v[8:11]
	v_mfma_f32_16x16x32_bf16 v[4:7], v[242:245], v[210:213], v[4:7]
	s_setprio 0
	s_add_i32 s0, s0, 2
	v_lshl_add_u64 v[62:63], v[62:63], 0, s[74:75]
	s_cmp_gt_u32 s0, s99
	v_mov_b64_e32 v[64:65], v[66:67]
	s_barrier
	s_cbranch_scc0 .LBB0_81
	v_cmp_gt_i32_e32 vcc, 24, v176
	v_mov_b32_e32 v2, 0x3000
	v_mov_b32_e32 v62, 0x1800
	v_cndmask_b32_e32 v2, v2, v62, vcc
	v_cmp_lt_i32_e32 vcc, 15, v176
	v_lshl_or_b32 v150, v74, 8, v154
	v_ashrrev_i32_e32 v151, 31, v150
	v_cndmask_b32_e32 v2, 0, v2, vcc
	v_lshlrev_b32_e32 v2, 2, v2
	v_lshl_add_u64 v[62:63], s[12:13], 0, v[2:3]
	v_lshl_add_u64 v[62:63], v[150:151], 2, v[62:63]
	global_load_dwordx4 v[82:85], v[62:63], off
	global_load_dwordx4 v[74:77], v[62:63], off offset:64
	global_load_dwordx4 v[66:69], v[62:63], off offset:512
	s_nop 0
	global_load_dwordx4 v[62:65], v[62:63], off offset:576
	s_cmp_eq_u32 s55, 0
	s_cselect_b64 s[6:7], -1, 0
	s_cmp_lg_u32 s55, 0
	s_mov_b64 s[40:41], 0xb0000
	s_cselect_b64 s[0:1], -1, 0
	v_add_u32_e32 v174, v37, v150
	v_mov_b32_e32 v175, v3
	v_lshlrev_b32_e32 v158, 8, v176
	v_ashrrev_i32_e32 v159, 31, v158
	v_lshlrev_b64 v[178:179], 12, v[158:159]
	v_lshl_add_u64 v[176:177], s[8:9], 0, v[178:179]
	s_and_b64 s[6:7], exec, s[6:7]
	s_cselect_b32 s7, s9, s35
	s_cselect_b32 s6, s8, s34
	v_lshl_add_u64 v[178:179], s[6:7], 0, v[178:179]
	s_and_b64 vcc, exec, s[0:1]
	s_cbranch_vccnz .Lrk_mul
	v_mov_b32_e32 v150, v174
	v_mov_b32_e32 v151, v3
	v_lshl_add_u64 v[152:153], v[150:151], 2, v[176:177]
	global_load_dwordx4 v[182:185], v[152:153], off
	global_load_dwordx4 v[186:189], v[152:153], off offset:64
	global_load_dwordx4 v[190:193], v[152:153], off offset:512
	global_load_dwordx4 v[194:197], v[152:153], off offset:576
	v_add_u32_e32 v150, 0x4000, v174
	v_mov_b32_e32 v151, v3
	v_lshl_add_u64 v[152:153], v[150:151], 2, v[176:177]
	global_load_dwordx4 v[198:201], v[152:153], off
	global_load_dwordx4 v[202:205], v[152:153], off offset:64
	global_load_dwordx4 v[206:209], v[152:153], off offset:512
	global_load_dwordx4 v[210:213], v[152:153], off offset:576
	v_add_u32_e32 v150, 0x8000, v174
	v_mov_b32_e32 v151, v3
	v_lshl_add_u64 v[152:153], v[150:151], 2, v[176:177]
	global_load_dwordx4 v[214:217], v[152:153], off
	global_load_dwordx4 v[234:237], v[152:153], off offset:64
	global_load_dwordx4 v[238:241], v[152:153], off offset:512
	global_load_dwordx4 v[242:245], v[152:153], off offset:576
	v_mov_b32_e32 v150, v174
	v_mov_b32_e32 v151, v3
	v_lshl_add_u64 v[158:159], v[150:151], 2, v[178:179]
	s_waitcnt vmcnt(11)
	v_pk_fma_f32 v[148:149], v[148:149], v[84:85], v[184:185]
	v_pk_fma_f32 v[146:147], v[146:147], v[82:83], v[182:183]
	global_store_dwordx4 v[158:159], v[146:149], off
	v_add_u32_e32 v150, 0xc000, v174
	v_mov_b32_e32 v151, v3
	v_lshl_add_u64 v[152:153], v[150:151], 2, v[176:177]
	global_load_dwordx4 v[182:185], v[152:153], off
	s_waitcnt vmcnt(12)
	v_pk_fma_f32 v[144:145], v[144:145], v[76:77], v[188:189]
	v_pk_fma_f32 v[142:143], v[142:143], v[74:75], v[186:187]
	global_store_dwordx4 v[158:159], v[142:145], off offset:64
	global_load_dwordx4 v[186:189], v[152:153], off offset:64
	s_waitcnt vmcnt(13)
	v_pk_fma_f32 v[140:141], v[140:141], v[68:69], v[192:193]
	v_pk_fma_f32 v[138:139], v[138:139], v[66:67], v[190:191]
	global_store_dwordx4 v[158:159], v[138:141], off offset:512
	global_load_dwordx4 v[190:193], v[152:153], off offset:512
	s_waitcnt vmcnt(14)
	v_pk_fma_f32 v[136:137], v[136:137], v[64:65], v[196:197]
	v_pk_fma_f32 v[134:135], v[134:135], v[62:63], v[194:195]
	global_store_dwordx4 v[158:159], v[134:137], off offset:576
	global_load_dwordx4 v[194:197], v[152:153], off offset:576
	v_add_u32_e32 v150, 0x4000, v174
	v_mov_b32_e32 v151, v3
	v_lshl_add_u64 v[158:159], v[150:151], 2, v[178:179]
	s_waitcnt vmcnt(15)
	v_pk_fma_f32 v[132:133], v[132:133], v[84:85], v[200:201]
	v_pk_fma_f32 v[130:131], v[130:131], v[82:83], v[198:199]
	global_store_dwordx4 v[158:159], v[130:133], off
	v_add_u32_e32 v150, 0x20000, v174
	v_mov_b32_e32 v151, v3
	v_lshl_add_u64 v[152:153], v[150:151], 2, v[176:177]
	global_load_dwordx4 v[198:201], v[152:153], off
	s_waitcnt vmcnt(16)
	v_pk_fma_f32 v[128:129], v[128:129], v[76:77], v[204:205]
	v_pk_fma_f32 v[126:127], v[126:127], v[74:75], v[202:203]
	global_store_dwordx4 v[158:159], v[126:129], off offset:64
	global_load_dwordx4 v[202:205], v[152:153], off offset:64
	s_waitcnt vmcnt(17)
	v_pk_fma_f32 v[124:125], v[124:125], v[68:69], v[208:209]
	v_pk_fma_f32 v[122:123], v[122:123], v[66:67], v[206:207]
	global_store_dwordx4 v[158:159], v[122:125], off offset:512
	global_load_dwordx4 v[206:209], v[152:153], off offset:512
	s_waitcnt vmcnt(18)
	v_pk_fma_f32 v[120:121], v[120:121], v[64:65], v[212:213]
	v_pk_fma_f32 v[118:119], v[118:119], v[62:63], v[210:211]
	global_store_dwordx4 v[158:159], v[118:121], off offset:576
	global_load_dwordx4 v[210:213], v[152:153], off offset:576
	v_add_u32_e32 v150, 0x8000, v174
	v_mov_b32_e32 v151, v3
	v_lshl_add_u64 v[158:159], v[150:151], 2, v[178:179]
	s_waitcnt vmcnt(19)
	v_pk_fma_f32 v[116:117], v[116:117], v[84:85], v[216:217]
	v_pk_fma_f32 v[114:115], v[114:115], v[82:83], v[214:215]
	global_store_dwordx4 v[158:159], v[114:117], off
	v_add_u32_e32 v150, 0x24000, v174
	v_mov_b32_e32 v151, v3
	v_lshl_add_u64 v[152:153], v[150:151], 2, v[176:177]
	global_load_dwordx4 v[214:217], v[152:153], off
	s_waitcnt vmcnt(20)
	v_pk_fma_f32 v[112:113], v[112:113], v[76:77], v[236:237]
	v_pk_fma_f32 v[110:111], v[110:111], v[74:75], v[234:235]
	global_store_dwordx4 v[158:159], v[110:113], off offset:64
	global_load_dwordx4 v[234:237], v[152:153], off offset:64
	s_waitcnt vmcnt(21)
	v_pk_fma_f32 v[108:109], v[108:109], v[68:69], v[240:241]
	v_pk_fma_f32 v[106:107], v[106:107], v[66:67], v[238:239]
	global_store_dwordx4 v[158:159], v[106:109], off offset:512
	global_load_dwordx4 v[238:241], v[152:153], off offset:512
	s_waitcnt vmcnt(22)
	v_pk_fma_f32 v[104:105], v[104:105], v[64:65], v[244:245]
	v_pk_fma_f32 v[102:103], v[102:103], v[62:63], v[242:243]
	global_store_dwordx4 v[158:159], v[102:105], off offset:576
	global_load_dwordx4 v[242:245], v[152:153], off offset:576
	v_add_u32_e32 v150, 0xc000, v174
	v_mov_b32_e32 v151, v3
	v_lshl_add_u64 v[158:159], v[150:151], 2, v[178:179]
	s_waitcnt vmcnt(22)
	v_pk_fma_f32 v[100:101], v[100:101], v[84:85], v[184:185]
	v_pk_fma_f32 v[98:99], v[98:99], v[82:83], v[182:183]
	global_store_dwordx4 v[158:159], v[98:101], off
	v_add_u32_e32 v150, 0x28000, v174
	v_mov_b32_e32 v151, v3
	v_lshl_add_u64 v[152:153], v[150:151], 2, v[176:177]
	global_load_dwordx4 v[182:185], v[152:153], off
	s_waitcnt vmcnt(22)
	v_pk_fma_f32 v[96:97], v[96:97], v[76:77], v[188:189]
	v_pk_fma_f32 v[94:95], v[94:95], v[74:75], v[186:187]
	global_store_dwordx4 v[158:159], v[94:97], off offset:64
	global_load_dwordx4 v[186:189], v[152:153], off offset:64
	s_waitcnt vmcnt(22)
	v_pk_fma_f32 v[92:93], v[92:93], v[68:69], v[192:193]
	v_pk_fma_f32 v[90:91], v[90:91], v[66:67], v[190:191]
	global_store_dwordx4 v[158:159], v[90:93], off offset:512
	global_load_dwordx4 v[190:193], v[152:153], off offset:512
	s_waitcnt vmcnt(22)
	v_pk_fma_f32 v[88:89], v[88:89], v[64:65], v[196:197]
	v_pk_fma_f32 v[86:87], v[86:87], v[62:63], v[194:195]
	global_store_dwordx4 v[158:159], v[86:89], off offset:576
	global_load_dwordx4 v[194:197], v[152:153], off offset:576
	v_add_u32_e32 v150, 0x20000, v174
	v_mov_b32_e32 v151, v3
	v_lshl_add_u64 v[158:159], v[150:151], 2, v[178:179]
	s_waitcnt vmcnt(22)
	v_pk_fma_f32 v[80:81], v[80:81], v[84:85], v[200:201]
	v_pk_fma_f32 v[78:79], v[78:79], v[82:83], v[198:199]
	global_store_dwordx4 v[158:159], v[78:81], off
	v_add_u32_e32 v150, 0x2c000, v174
	v_mov_b32_e32 v151, v3
	v_lshl_add_u64 v[152:153], v[150:151], 2, v[176:177]
	global_load_dwordx4 v[198:201], v[152:153], off
	s_waitcnt vmcnt(22)
	v_pk_fma_f32 v[72:73], v[72:73], v[76:77], v[204:205]
	v_pk_fma_f32 v[70:71], v[70:71], v[74:75], v[202:203]
	global_store_dwordx4 v[158:159], v[70:73], off offset:64
	global_load_dwordx4 v[202:205], v[152:153], off offset:64
	s_waitcnt vmcnt(22)
	v_pk_fma_f32 v[60:61], v[60:61], v[68:69], v[208:209]
	v_pk_fma_f32 v[58:59], v[58:59], v[66:67], v[206:207]
	global_store_dwordx4 v[158:159], v[58:61], off offset:512
	global_load_dwordx4 v[206:209], v[152:153], off offset:512
	s_waitcnt vmcnt(22)
	v_pk_fma_f32 v[56:57], v[56:57], v[64:65], v[212:213]
	v_pk_fma_f32 v[54:55], v[54:55], v[62:63], v[210:211]
	global_store_dwordx4 v[158:159], v[54:57], off offset:576
	global_load_dwordx4 v[210:213], v[152:153], off offset:576
	v_add_u32_e32 v150, 0x24000, v174
	v_mov_b32_e32 v151, v3
	v_lshl_add_u64 v[158:159], v[150:151], 2, v[178:179]
	s_waitcnt vmcnt(22)
	v_pk_fma_f32 v[52:53], v[52:53], v[84:85], v[216:217]
	v_pk_fma_f32 v[50:51], v[50:51], v[82:83], v[214:215]
	global_store_dwordx4 v[158:159], v[50:53], off
	s_waitcnt vmcnt(21)
	v_pk_fma_f32 v[48:49], v[48:49], v[76:77], v[236:237]
	v_pk_fma_f32 v[46:47], v[46:47], v[74:75], v[234:235]
	global_store_dwordx4 v[158:159], v[46:49], off offset:64
	s_waitcnt vmcnt(20)
	v_pk_fma_f32 v[44:45], v[44:45], v[68:69], v[240:241]
	v_pk_fma_f32 v[42:43], v[42:43], v[66:67], v[238:239]
	global_store_dwordx4 v[158:159], v[42:45], off offset:512
	s_waitcnt vmcnt(19)
	v_pk_fma_f32 v[40:41], v[40:41], v[64:65], v[244:245]
	v_pk_fma_f32 v[38:39], v[38:39], v[62:63], v[242:243]
	global_store_dwordx4 v[158:159], v[38:41], off offset:576
	v_add_u32_e32 v150, 0x28000, v174
	v_mov_b32_e32 v151, v3
	v_lshl_add_u64 v[158:159], v[150:151], 2, v[178:179]
	s_waitcnt vmcnt(18)
	v_pk_fma_f32 v[34:35], v[34:35], v[84:85], v[184:185]
	v_pk_fma_f32 v[32:33], v[32:33], v[82:83], v[182:183]
	global_store_dwordx4 v[158:159], v[32:35], off
	s_waitcnt vmcnt(17)
	v_pk_fma_f32 v[30:31], v[30:31], v[76:77], v[188:189]
	v_pk_fma_f32 v[28:29], v[28:29], v[74:75], v[186:187]
	global_store_dwordx4 v[158:159], v[28:31], off offset:64
	s_waitcnt vmcnt(16)
	v_pk_fma_f32 v[26:27], v[26:27], v[68:69], v[192:193]
	v_pk_fma_f32 v[24:25], v[24:25], v[66:67], v[190:191]
	global_store_dwordx4 v[158:159], v[24:27], off offset:512
	s_waitcnt vmcnt(15)
	v_pk_fma_f32 v[22:23], v[22:23], v[64:65], v[196:197]
	v_pk_fma_f32 v[20:21], v[20:21], v[62:63], v[194:195]
	global_store_dwordx4 v[158:159], v[20:23], off offset:576
	v_add_u32_e32 v150, 0x2c000, v174
	v_mov_b32_e32 v151, v3
	v_lshl_add_u64 v[158:159], v[150:151], 2, v[178:179]
	s_waitcnt vmcnt(14)
	v_pk_fma_f32 v[18:19], v[18:19], v[84:85], v[200:201]
	v_pk_fma_f32 v[16:17], v[16:17], v[82:83], v[198:199]
	global_store_dwordx4 v[158:159], v[16:19], off
	s_waitcnt vmcnt(13)
	v_pk_fma_f32 v[14:15], v[14:15], v[76:77], v[204:205]
	v_pk_fma_f32 v[12:13], v[12:13], v[74:75], v[202:203]
	global_store_dwordx4 v[158:159], v[12:15], off offset:64
	s_waitcnt vmcnt(12)
	v_pk_fma_f32 v[10:11], v[10:11], v[68:69], v[208:209]
	v_pk_fma_f32 v[8:9], v[8:9], v[66:67], v[206:207]
	global_store_dwordx4 v[158:159], v[8:11], off offset:512
	s_waitcnt vmcnt(11)
	v_pk_fma_f32 v[6:7], v[6:7], v[64:65], v[212:213]
	v_pk_fma_f32 v[4:5], v[4:5], v[62:63], v[210:211]
	global_store_dwordx4 v[158:159], v[4:7], off offset:576
	s_branch .Lrk_tail
